# residual GEMM epilogues: xold loads pipelined three groups deep with counted waits, all 32 stores issued at the end
# baseline (speedup 1.0000x reference)
; #define PG8_STAGE(bufoff, gbase, voff) do { _Pragma("unroll") for (int _i = 0; _i < 2; ++_i) \
;         __builtin_amdgcn_global_load_lds((const unsigned*)((const char*)(gbase) + (voff)[_i]), (LAS unsigned*)(lds + (bufoff) + ldsw + _i * 8192), 16, 0, 0); } while (0)
; #define PG8_LDA(dst, b, h) do { _Pragma("unroll") for (int m = 0; m < 4; ++m) _Pragma("unroll") for (int k = 0; k < 2; ++k) dst[m][k] = *(const LAS bf16x8*)(lds + PG8_SA(b, h) + aoff + m * 2048 + k * 1024); } while (0)
; #define PG8_LDB(dst, b, h) do { _Pragma("unroll") for (int n = 0; n < 2; ++n) _Pragma("unroll") for (int k = 0; k < 2; ++k) dst[n][k] = *(const LAS bf16x8*)(lds + PG8_SB(b, h) + boff + n * 2048 + k * 1024); } while (0)
; #define PG8_MMA(ai, bj, At, Bt) do { __builtin_amdgcn_s_setprio(1); _Pragma("unroll") for (int m = 0; m < 4; ++m) _Pragma("unroll") for (int n = 0; n < 2; ++n) _Pragma("unroll") for (int k = 0; k < 2; ++k) \
;         acc[ai][bj][m][n] = __builtin_amdgcn_mfma_f32_16x16x32_bf16(Bt[n][k], At[m][k], acc[ai][bj][m][n], 0, 0, 0); __builtin_amdgcn_s_setprio(0); } while (0)
; #define PG8_BAR __builtin_amdgcn_s_barrier()
; template <class AMap, class Epi>
; DI void gemm_phase(LAS unsigned char* lds, const u16* Aptr, const u16* Btptr, int K, const StaticOrder& SO, const Epi& E) {
;     ...
;     for (int t = 0; t < nt; t += 2) {
;       const bool last = (t == nt - 2);
;       const char* a1 = cA + (size_t)(t + 1) * kstep;
;       const char* a2 = last ? nA : cA + (size_t)(t + 2) * kstep; const char* b2 = last ? nB : cB + (size_t)(t + 2) * kstep;
;       const char* a3 = a2 + kstep; const char* b3 = b2 + kstep;
;       PG8_LDB(B0, 0, 0); PG8_SCHED; PG8_LDA(At, 0, 0); PG8_STAGE(PG8_SA(1, 1), a1 + hstepA, voffA);
;       PG8_WAIT_L(8); PG8_BAR; PG8_WAIT_L(0); PG8_MMA(0, 0, At, B0); PG8_BAR; PG8_SCHED;
;       PG8_LDB(B1, 0, 1); PG8_STAGE(PG8_SB(0, 0), b2, voffB);
;       PG8_BAR; PG8_WAIT_L(0); PG8_MMA(0, 1, At, B1); PG8_BAR;
;       PG8_LDA(At, 0, 1); PG8_STAGE(PG8_SA(0, 0), a2, voffA);
;       PG8_BAR; PG8_WAIT_L(0); PG8_MMA(1, 0, At, B0); PG8_BAR; PG8_SCHED;
;       PG8_STAGE(PG8_SB(0, 1), b2 + hstepB, voffB);
;       PG8_WAIT_V(6); PG8_BAR; PG8_MMA(1, 1, At, B1); PG8_BAR;
;       PG8_LDB(B0, 1, 0); PG8_SCHED; PG8_LDA(At, 1, 0); PG8_STAGE(PG8_SA(0, 1), a2 + hstepA, voffA);
;       PG8_WAIT_L(8); PG8_BAR; PG8_WAIT_L(0); PG8_MMA(0, 0, At, B0); PG8_BAR; PG8_SCHED;
.LBB0_538:
	s_add_u32 s36, s16, 0x100
	s_addc_u32 s37, s17, 0
	s_add_i32 s60, 0, 0x10000
	v_add_u32_e32 v112, s60, v173
	ds_read_b128 v[100:103], v112
	ds_read_b128 v[104:107], v112 offset:1024
	ds_read_b128 v[108:111], v112 offset:2048
	ds_read_b128 v[112:115], v112 offset:3072
	s_cmp_eq_u32 s59, 12
	s_cselect_b32 s49, s35, s37
	s_cselect_b32 s48, s55, s36
	s_cselect_b32 s47, s31, s58
	s_cselect_b32 s46, s56, s57
	v_lshl_add_u64 v[204:205], s[16:17], 0, v[164:165]
	s_add_i32 m0, s19, 0xc000
	ds_read_b128 v[168:171], v175
	ds_read_b128 v[176:179], v175 offset:1024
	ds_read_b128 v[180:183], v175 offset:2048
	ds_read_b128 v[184:187], v175 offset:3072
	ds_read_b128 v[188:191], v175 offset:4096
	ds_read_b128 v[192:195], v175 offset:5120
	ds_read_b128 v[196:199], v175 offset:6144
	ds_read_b128 v[200:203], v175 offset:7168
	global_load_lds_dwordx4 v[204:205], off
	v_lshl_add_u64 v[204:205], s[16:17], 0, v[166:167]
	s_add_i32 m0, s19, 0xe000
	s_nop 0
	global_load_lds_dwordx4 v[204:205], off
	s_waitcnt lgkmcnt(8)
	s_barrier
	s_waitcnt lgkmcnt(0)
	s_setprio 1
	s_waitcnt lgkmcnt(0)
	v_mfma_f32_16x16x32_bf16 v[160:163], v[100:103], v[168:171], v[160:163]
	v_mfma_f32_16x16x32_bf16 v[156:159], v[108:111], v[168:171], v[156:159]
	v_mfma_f32_16x16x32_bf16 v[144:147], v[100:103], v[180:183], v[144:147]
	v_mfma_f32_16x16x32_bf16 v[140:143], v[108:111], v[180:183], v[140:143]
	v_mfma_f32_16x16x32_bf16 v[128:131], v[100:103], v[188:191], v[128:131]
	v_mfma_f32_16x16x32_bf16 v[124:127], v[108:111], v[188:191], v[124:127]
	v_mfma_f32_16x16x32_bf16 v[96:99], v[100:103], v[196:199], v[96:99]
	v_mfma_f32_16x16x32_bf16 v[92:95], v[108:111], v[196:199], v[92:95]
	v_mfma_f32_16x16x32_bf16 v[160:163], v[104:107], v[176:179], v[160:163]
	v_mfma_f32_16x16x32_bf16 v[156:159], v[112:115], v[176:179], v[156:159]
	v_mfma_f32_16x16x32_bf16 v[144:147], v[104:107], v[184:187], v[144:147]
	v_mfma_f32_16x16x32_bf16 v[140:143], v[112:115], v[184:187], v[140:143]
	v_mfma_f32_16x16x32_bf16 v[128:131], v[104:107], v[192:195], v[128:131]
	v_mfma_f32_16x16x32_bf16 v[124:127], v[112:115], v[192:195], v[124:127]
	v_mfma_f32_16x16x32_bf16 v[96:99], v[104:107], v[200:203], v[96:99]
	v_mfma_f32_16x16x32_bf16 v[92:95], v[112:115], v[200:203], v[92:95]
	s_setprio 0
	s_barrier
	s_add_i32 s61, 0, 0x14000
	s_add_i32 s16, s60, s18
	v_add_u32_e32 v216, s61, v173
	v_lshl_add_u64 v[220:221], s[46:47], 0, v[0:1]
	s_mov_b32 m0, s16
	ds_read_b128 v[204:207], v216
	ds_read_b128 v[208:211], v216 offset:1024
	ds_read_b128 v[212:215], v216 offset:2048
	ds_read_b128 v[216:219], v216 offset:3072
	global_load_lds_dwordx4 v[220:221], off
	v_lshl_add_u64 v[222:223], s[46:47], 0, v[14:15]
	s_add_i32 m0, s16, 0x2000
	s_nop 0
	global_load_lds_dwordx4 v[222:223], off
	s_barrier
	s_waitcnt lgkmcnt(0)
	s_setprio 1
	s_waitcnt lgkmcnt(0)
	v_mfma_f32_16x16x32_bf16 v[152:155], v[204:207], v[168:171], v[152:155]
	v_mfma_f32_16x16x32_bf16 v[148:151], v[212:215], v[168:171], v[148:151]
	v_mfma_f32_16x16x32_bf16 v[136:139], v[204:207], v[180:183], v[136:139]
	v_mfma_f32_16x16x32_bf16 v[132:135], v[212:215], v[180:183], v[132:135]
	v_mfma_f32_16x16x32_bf16 v[120:123], v[204:207], v[188:191], v[120:123]
	v_mfma_f32_16x16x32_bf16 v[116:119], v[212:215], v[188:191], v[116:119]
	v_mfma_f32_16x16x32_bf16 v[88:91], v[204:207], v[196:199], v[88:91]
	v_mfma_f32_16x16x32_bf16 v[84:87], v[212:215], v[196:199], v[84:87]
	v_mfma_f32_16x16x32_bf16 v[152:155], v[208:211], v[176:179], v[152:155]
	v_mfma_f32_16x16x32_bf16 v[148:151], v[216:219], v[176:179], v[148:151]
	v_mfma_f32_16x16x32_bf16 v[136:139], v[208:211], v[184:187], v[136:139]
	v_mfma_f32_16x16x32_bf16 v[132:135], v[216:219], v[184:187], v[132:135]
	v_mfma_f32_16x16x32_bf16 v[120:123], v[208:211], v[192:195], v[120:123]
	v_mfma_f32_16x16x32_bf16 v[116:119], v[216:219], v[192:195], v[116:119]
	v_mfma_f32_16x16x32_bf16 v[88:91], v[208:211], v[200:203], v[88:91]
	v_mfma_f32_16x16x32_bf16 v[84:87], v[216:219], v[200:203], v[84:87]
	s_setprio 0
	s_mov_b32 m0, s19
	v_lshl_add_u64 v[236:237], s[48:49], 0, v[0:1]
	s_barrier
	ds_read_b128 v[168:171], v175 offset:16384
	ds_read_b128 v[176:179], v175 offset:17408
	ds_read_b128 v[180:183], v175 offset:18432
	ds_read_b128 v[184:187], v175 offset:19456
	ds_read_b128 v[188:191], v175 offset:20480
	ds_read_b128 v[192:195], v175 offset:21504
	ds_read_b128 v[196:199], v175 offset:22528
	ds_read_b128 v[200:203], v175 offset:23552
	global_load_lds_dwordx4 v[236:237], off
	v_lshl_add_u64 v[238:239], s[48:49], 0, v[14:15]
	s_mov_b32 m0, s20
	s_nop 0
	global_load_lds_dwordx4 v[238:239], off
	s_barrier
	s_waitcnt lgkmcnt(0)
	s_setprio 1
	s_waitcnt lgkmcnt(0)
	v_mfma_f32_16x16x32_bf16 v[80:83], v[100:103], v[168:171], v[80:83]
	v_mfma_f32_16x16x32_bf16 v[76:79], v[108:111], v[168:171], v[76:79]
	v_mfma_f32_16x16x32_bf16 v[64:67], v[100:103], v[180:183], v[64:67]
	v_mfma_f32_16x16x32_bf16 v[60:63], v[108:111], v[180:183], v[60:63]
	v_mfma_f32_16x16x32_bf16 v[48:51], v[100:103], v[188:191], v[48:51]
	v_mfma_f32_16x16x32_bf16 v[44:47], v[108:111], v[188:191], v[44:47]
	v_mfma_f32_16x16x32_bf16 v[32:35], v[100:103], v[196:199], v[32:35]
	v_mfma_f32_16x16x32_bf16 v[10:13], v[108:111], v[196:199], v[10:13]
	v_mfma_f32_16x16x32_bf16 v[80:83], v[104:107], v[176:179], v[80:83]
	v_mfma_f32_16x16x32_bf16 v[76:79], v[112:115], v[176:179], v[76:79]
	v_mfma_f32_16x16x32_bf16 v[64:67], v[104:107], v[184:187], v[64:67]
	v_mfma_f32_16x16x32_bf16 v[60:63], v[112:115], v[184:187], v[60:63]
	v_mfma_f32_16x16x32_bf16 v[48:51], v[104:107], v[192:195], v[48:51]
	v_mfma_f32_16x16x32_bf16 v[44:47], v[112:115], v[192:195], v[44:47]
	v_mfma_f32_16x16x32_bf16 v[32:35], v[104:107], v[200:203], v[32:35]
	v_mfma_f32_16x16x32_bf16 v[10:13], v[112:115], v[200:203], v[10:13]
	s_setprio 0
	s_barrier
; #define PG8_STAGE(bufoff, gbase, voff) do { _Pragma("unroll") for (int _i = 0; _i < 2; ++_i) \
;         __builtin_amdgcn_global_load_lds((const unsigned*)((const char*)(gbase) + (voff)[_i]), (LAS unsigned*)(lds + (bufoff) + ldsw + _i * 8192), 16, 0, 0); } while (0)
; #define PG8_LDA(dst, b, h) do { _Pragma("unroll") for (int m = 0; m < 4; ++m) _Pragma("unroll") for (int k = 0; k < 2; ++k) dst[m][k] = *(const LAS bf16x8*)(lds + PG8_SA(b, h) + aoff + m * 2048 + k * 1024); } while (0)
; #define PG8_LDB(dst, b, h) do { _Pragma("unroll") for (int n = 0; n < 2; ++n) _Pragma("unroll") for (int k = 0; k < 2; ++k) dst[n][k] = *(const LAS bf16x8*)(lds + PG8_SB(b, h) + boff + n * 2048 + k * 1024); } while (0)
; #define PG8_MMA(ai, bj, At, Bt) do { __builtin_amdgcn_s_setprio(1); _Pragma("unroll") for (int m = 0; m < 4; ++m) _Pragma("unroll") for (int n = 0; n < 2; ++n) _Pragma("unroll") for (int k = 0; k < 2; ++k) \
;         acc[ai][bj][m][n] = __builtin_amdgcn_mfma_f32_16x16x32_bf16(Bt[n][k], At[m][k], acc[ai][bj][m][n], 0, 0, 0); __builtin_amdgcn_s_setprio(0); } while (0)
; #define PG8_WAIT_V(n) asm volatile("s_waitcnt vmcnt(" #n ")" ::: "memory")
; #define PG8_WAIT_L(n) asm volatile("s_waitcnt lgkmcnt(" #n ")" ::: "memory")
; #define PG8_BAR __builtin_amdgcn_s_barrier()
; #define PG8_SCHED __builtin_amdgcn_sched_barrier(0)
; template <class AMap, class Epi>
; DI void gemm_phase(LAS unsigned char* lds, const u16* Aptr, const u16* Btptr, int K, const StaticOrder& SO, const Epi& E) {
;     ...
;       PG8_WAIT_V(6); PG8_BAR; PG8_MMA(1, 1, At, B1); PG8_BAR;
;       PG8_LDB(B0, 1, 0); PG8_SCHED; PG8_LDA(At, 1, 0); PG8_STAGE(PG8_SA(0, 1), a2 + hstepA, voffA);
;       PG8_WAIT_L(8); PG8_BAR; PG8_WAIT_L(0); PG8_MMA(0, 0, At, B0); PG8_BAR; PG8_SCHED;
;       PG8_LDB(B1, 1, 1); PG8_STAGE(PG8_SB(1, 0), b3, voffB);
;       PG8_BAR; PG8_WAIT_L(0); PG8_MMA(0, 1, At, B1); PG8_BAR;
;       PG8_LDA(At, 1, 1); PG8_STAGE(PG8_SA(1, 0), a3, voffA);
;       PG8_BAR; PG8_WAIT_L(0); PG8_MMA(1, 0, At, B0); PG8_BAR; PG8_SCHED;
	s_add_u32 s16, s46, 0x40000
	s_addc_u32 s17, s47, 0
	s_add_i32 s60, s61, s18
	v_lshl_add_u64 v[100:101], s[16:17], 0, v[0:1]
	s_mov_b32 m0, s60
	s_nop 0
	global_load_lds_dwordx4 v[100:101], off
	v_lshl_add_u64 v[100:101], s[16:17], 0, v[14:15]
	s_add_i32 m0, s60, 0x2000
	s_nop 0
	global_load_lds_dwordx4 v[100:101], off
	s_waitcnt vmcnt(6)
	s_barrier
	s_setprio 1
	v_mfma_f32_16x16x32_bf16 v[72:75], v[204:207], v[168:171], v[72:75]
	v_mfma_f32_16x16x32_bf16 v[68:71], v[212:215], v[168:171], v[68:71]
	v_mfma_f32_16x16x32_bf16 v[56:59], v[204:207], v[180:183], v[56:59]
	v_mfma_f32_16x16x32_bf16 v[52:55], v[212:215], v[180:183], v[52:55]
	v_mfma_f32_16x16x32_bf16 v[40:43], v[204:207], v[188:191], v[40:43]
	v_mfma_f32_16x16x32_bf16 v[36:39], v[212:215], v[188:191], v[36:39]
	v_mfma_f32_16x16x32_bf16 v[6:9], v[204:207], v[196:199], v[6:9]
	v_mfma_f32_16x16x32_bf16 v[2:5], v[212:215], v[196:199], v[2:5]
	v_mfma_f32_16x16x32_bf16 v[72:75], v[208:211], v[176:179], v[72:75]
	v_mfma_f32_16x16x32_bf16 v[68:71], v[216:219], v[176:179], v[68:71]
	v_mfma_f32_16x16x32_bf16 v[56:59], v[208:211], v[184:187], v[56:59]
	v_mfma_f32_16x16x32_bf16 v[52:55], v[216:219], v[184:187], v[52:55]
	v_mfma_f32_16x16x32_bf16 v[40:43], v[208:211], v[192:195], v[40:43]
	v_mfma_f32_16x16x32_bf16 v[36:39], v[216:219], v[192:195], v[36:39]
	v_mfma_f32_16x16x32_bf16 v[6:9], v[208:211], v[200:203], v[6:9]
	v_mfma_f32_16x16x32_bf16 v[2:5], v[216:219], v[200:203], v[2:5]
	s_setprio 0
	s_add_i32 s60, 0, 0x18000
	v_add_u32_e32 v112, s60, v173
	s_barrier
	ds_read_b128 v[100:103], v112
	ds_read_b128 v[104:107], v112 offset:1024
	ds_read_b128 v[108:111], v112 offset:2048
	ds_read_b128 v[112:115], v112 offset:3072
	s_add_u32 s16, s48, 0x40000
	s_addc_u32 s17, s49, 0
	s_mov_b32 m0, s21
	v_lshl_add_u64 v[204:205], s[16:17], 0, v[0:1]
	ds_read_b128 v[168:171], v175 offset:32768
	ds_read_b128 v[176:179], v175 offset:33792
	ds_read_b128 v[180:183], v175 offset:34816
	ds_read_b128 v[184:187], v175 offset:35840
	ds_read_b128 v[188:191], v175 offset:36864
	ds_read_b128 v[192:195], v175 offset:37888
	ds_read_b128 v[196:199], v175 offset:38912
	ds_read_b128 v[200:203], v175 offset:39936
	global_load_lds_dwordx4 v[204:205], off
	v_lshl_add_u64 v[204:205], s[16:17], 0, v[14:15]
	s_mov_b32 m0, s23
	s_nop 0
	global_load_lds_dwordx4 v[204:205], off
	s_waitcnt lgkmcnt(8)
	s_barrier
	s_waitcnt lgkmcnt(0)
	s_setprio 1
	s_waitcnt lgkmcnt(0)
	v_mfma_f32_16x16x32_bf16 v[160:163], v[100:103], v[168:171], v[160:163]
	v_mfma_f32_16x16x32_bf16 v[156:159], v[108:111], v[168:171], v[156:159]
	v_mfma_f32_16x16x32_bf16 v[144:147], v[100:103], v[180:183], v[144:147]
	v_mfma_f32_16x16x32_bf16 v[140:143], v[108:111], v[180:183], v[140:143]
	v_mfma_f32_16x16x32_bf16 v[128:131], v[100:103], v[188:191], v[128:131]
	v_mfma_f32_16x16x32_bf16 v[124:127], v[108:111], v[188:191], v[124:127]
	v_mfma_f32_16x16x32_bf16 v[96:99], v[100:103], v[196:199], v[96:99]
	v_mfma_f32_16x16x32_bf16 v[92:95], v[108:111], v[196:199], v[92:95]
	v_mfma_f32_16x16x32_bf16 v[160:163], v[104:107], v[176:179], v[160:163]
	v_mfma_f32_16x16x32_bf16 v[156:159], v[112:115], v[176:179], v[156:159]
	v_mfma_f32_16x16x32_bf16 v[144:147], v[104:107], v[184:187], v[144:147]
	v_mfma_f32_16x16x32_bf16 v[140:143], v[112:115], v[184:187], v[140:143]
	v_mfma_f32_16x16x32_bf16 v[128:131], v[104:107], v[192:195], v[128:131]
	v_mfma_f32_16x16x32_bf16 v[124:127], v[112:115], v[192:195], v[124:127]
	v_mfma_f32_16x16x32_bf16 v[96:99], v[104:107], v[200:203], v[96:99]
	v_mfma_f32_16x16x32_bf16 v[92:95], v[112:115], v[200:203], v[92:95]
	s_setprio 0
	s_barrier
	s_add_i32 s48, 0, 0x1c000
	s_add_i32 s16, s60, s18
	v_add_u32_e32 v216, s48, v173
	v_lshl_add_u64 v[220:221], v[220:221], 0, s[14:15]
	s_mov_b32 m0, s16
	ds_read_b128 v[204:207], v216
	ds_read_b128 v[208:211], v216 offset:1024
	ds_read_b128 v[212:215], v216 offset:2048
	ds_read_b128 v[216:219], v216 offset:3072
	global_load_lds_dwordx4 v[220:221], off
	v_lshl_add_u64 v[220:221], v[222:223], 0, s[14:15]
	s_add_i32 m0, s16, 0x2000
	s_nop 0
	global_load_lds_dwordx4 v[220:221], off
	s_barrier
	s_waitcnt lgkmcnt(0)
	s_setprio 1
	s_waitcnt lgkmcnt(0)
	v_mfma_f32_16x16x32_bf16 v[152:155], v[204:207], v[168:171], v[152:155]
	v_mfma_f32_16x16x32_bf16 v[148:151], v[212:215], v[168:171], v[148:151]
	v_mfma_f32_16x16x32_bf16 v[136:139], v[204:207], v[180:183], v[136:139]
	v_mfma_f32_16x16x32_bf16 v[132:135], v[212:215], v[180:183], v[132:135]
	v_mfma_f32_16x16x32_bf16 v[120:123], v[204:207], v[188:191], v[120:123]
	v_mfma_f32_16x16x32_bf16 v[116:119], v[212:215], v[188:191], v[116:119]
	v_mfma_f32_16x16x32_bf16 v[88:91], v[204:207], v[196:199], v[88:91]
	v_mfma_f32_16x16x32_bf16 v[84:87], v[212:215], v[196:199], v[84:87]
	v_mfma_f32_16x16x32_bf16 v[152:155], v[208:211], v[176:179], v[152:155]
	v_mfma_f32_16x16x32_bf16 v[148:151], v[216:219], v[176:179], v[148:151]
	v_mfma_f32_16x16x32_bf16 v[136:139], v[208:211], v[184:187], v[136:139]
	v_mfma_f32_16x16x32_bf16 v[132:135], v[216:219], v[184:187], v[132:135]
	v_mfma_f32_16x16x32_bf16 v[120:123], v[208:211], v[192:195], v[120:123]
	v_mfma_f32_16x16x32_bf16 v[116:119], v[216:219], v[192:195], v[116:119]
	v_mfma_f32_16x16x32_bf16 v[88:91], v[208:211], v[200:203], v[88:91]
	v_mfma_f32_16x16x32_bf16 v[84:87], v[216:219], v[200:203], v[84:87]
	s_setprio 0
	s_mov_b32 m0, s50
	v_lshl_add_u64 v[220:221], v[236:237], 0, s[14:15]
	s_barrier
; #define PG8_STAGE(bufoff, gbase, voff) do { _Pragma("unroll") for (int _i = 0; _i < 2; ++_i) \
;         __builtin_amdgcn_global_load_lds((const unsigned*)((const char*)(gbase) + (voff)[_i]), (LAS unsigned*)(lds + (bufoff) + ldsw + _i * 8192), 16, 0, 0); } while (0)
; #define PG8_LDA(dst, b, h) do { _Pragma("unroll") for (int m = 0; m < 4; ++m) _Pragma("unroll") for (int k = 0; k < 2; ++k) dst[m][k] = *(const LAS bf16x8*)(lds + PG8_SA(b, h) + aoff + m * 2048 + k * 1024); } while (0)
; #define PG8_MMA(ai, bj, At, Bt) do { __builtin_amdgcn_s_setprio(1); _Pragma("unroll") for (int m = 0; m < 4; ++m) _Pragma("unroll") for (int n = 0; n < 2; ++n) _Pragma("unroll") for (int k = 0; k < 2; ++k) \
;         acc[ai][bj][m][n] = __builtin_amdgcn_mfma_f32_16x16x32_bf16(Bt[n][k], At[m][k], acc[ai][bj][m][n], 0, 0, 0); __builtin_amdgcn_s_setprio(0); } while (0)
; #define PG8_WAIT_V(n) asm volatile("s_waitcnt vmcnt(" #n ")" ::: "memory")
; #define PG8_WAIT_L(n) asm volatile("s_waitcnt lgkmcnt(" #n ")" ::: "memory")
; #define PG8_BAR __builtin_amdgcn_s_barrier()
; template <class AMap, class Epi>
; DI void gemm_phase(LAS unsigned char* lds, const u16* Aptr, const u16* Btptr, int K, const StaticOrder& SO, const Epi& E) {
;     ...
;       PG8_BAR; PG8_WAIT_L(0); PG8_MMA(0, 1, At, B1); PG8_BAR;
;       PG8_LDA(At, 1, 1); PG8_STAGE(PG8_SA(1, 0), a3, voffA);
;       PG8_BAR; PG8_WAIT_L(0); PG8_MMA(1, 0, At, B0); PG8_BAR; PG8_SCHED;
;       PG8_STAGE(PG8_SB(1, 1), b3 + hstepB, voffB);
;       PG8_WAIT_V(6); PG8_BAR; PG8_MMA(1, 1, At, B1); PG8_BAR;
;   DI void operator()(const f32x4 (&acc)[2][2][4][2], const pg8::Unit& u, int wr, int wc, int fr, int fq) const {
;     const int b = (u.pm * 256) >> 14;
;     const int col0 = u.pn * 256 + wc * 32 + 4 * fq;
;     f32x4 gv[2][2];
; #pragma unroll
;     for (int bj = 0; bj < 2; ++bj)
; #pragma unroll
;       for (int n = 0; n < 2; ++n) gv[bj][n] = *(const f32x4*)(gate + b * 6144 + col0 + bj * 128 + n * 16);
; #pragma unroll
;     for (int ai = 0; ai < 2; ++ai)
; #pragma unroll
;       for (int m = 0; m < 4; ++m) {
;         const size_t off = (size_t)(u.pm * 256 + ai * 128 + wr * 64 + m * 16 + fr) * 1024 + col0;
;         f32x4 xo[2][2];
; #pragma unroll
;         for (int bj = 0; bj < 2; ++bj)
; #pragma unroll
;           for (int n = 0; n < 2; ++n) xo[bj][n] = *(const f32x4*)(xold + off + bj * 128 + n * 16);
	ds_read_b128 v[168:171], v175 offset:49152
	ds_read_b128 v[176:179], v175 offset:50176
	ds_read_b128 v[180:183], v175 offset:51200
	ds_read_b128 v[184:187], v175 offset:52224
	ds_read_b128 v[188:191], v175 offset:53248
	ds_read_b128 v[192:195], v175 offset:54272
	ds_read_b128 v[196:199], v175 offset:55296
	ds_read_b128 v[200:203], v175 offset:56320
	global_load_lds_dwordx4 v[220:221], off
	v_lshl_add_u64 v[220:221], v[238:239], 0, s[14:15]
	s_mov_b32 m0, s51
	s_nop 0
	global_load_lds_dwordx4 v[220:221], off
	s_barrier
	s_waitcnt lgkmcnt(0)
	s_setprio 1
	s_waitcnt lgkmcnt(0)
	v_mfma_f32_16x16x32_bf16 v[80:83], v[100:103], v[168:171], v[80:83]
	v_mfma_f32_16x16x32_bf16 v[76:79], v[108:111], v[168:171], v[76:79]
	v_mfma_f32_16x16x32_bf16 v[64:67], v[100:103], v[180:183], v[64:67]
	v_mfma_f32_16x16x32_bf16 v[60:63], v[108:111], v[180:183], v[60:63]
	v_mfma_f32_16x16x32_bf16 v[48:51], v[100:103], v[188:191], v[48:51]
	v_mfma_f32_16x16x32_bf16 v[44:47], v[108:111], v[188:191], v[44:47]
	v_mfma_f32_16x16x32_bf16 v[32:35], v[100:103], v[196:199], v[32:35]
	v_mfma_f32_16x16x32_bf16 v[10:13], v[108:111], v[196:199], v[10:13]
	v_mfma_f32_16x16x32_bf16 v[80:83], v[104:107], v[176:179], v[80:83]
	v_mfma_f32_16x16x32_bf16 v[76:79], v[112:115], v[176:179], v[76:79]
	v_mfma_f32_16x16x32_bf16 v[64:67], v[104:107], v[184:187], v[64:67]
	v_mfma_f32_16x16x32_bf16 v[60:63], v[112:115], v[184:187], v[60:63]
	v_mfma_f32_16x16x32_bf16 v[48:51], v[104:107], v[192:195], v[48:51]
	v_mfma_f32_16x16x32_bf16 v[44:47], v[112:115], v[192:195], v[44:47]
	v_mfma_f32_16x16x32_bf16 v[32:35], v[104:107], v[200:203], v[32:35]
	v_mfma_f32_16x16x32_bf16 v[10:13], v[112:115], v[200:203], v[10:13]
	s_setprio 0
	s_barrier
	s_add_u32 s16, s46, 0x40080
	s_addc_u32 s17, s47, 0
	s_add_i32 s46, s48, s18
	v_lshl_add_u64 v[100:101], s[16:17], 0, v[0:1]
	s_mov_b32 m0, s46
	s_nop 0
	global_load_lds_dwordx4 v[100:101], off
	v_lshl_add_u64 v[100:101], s[16:17], 0, v[14:15]
	s_add_i32 m0, s46, 0x2000
	s_nop 0
	global_load_lds_dwordx4 v[100:101], off
	s_waitcnt vmcnt(6)
	s_barrier
	s_setprio 1
	v_mfma_f32_16x16x32_bf16 v[72:75], v[204:207], v[168:171], v[72:75]
	v_mfma_f32_16x16x32_bf16 v[68:71], v[212:215], v[168:171], v[68:71]
	v_mfma_f32_16x16x32_bf16 v[56:59], v[204:207], v[180:183], v[56:59]
	v_mfma_f32_16x16x32_bf16 v[52:55], v[212:215], v[180:183], v[52:55]
	v_mfma_f32_16x16x32_bf16 v[40:43], v[204:207], v[188:191], v[40:43]
	v_mfma_f32_16x16x32_bf16 v[36:39], v[212:215], v[188:191], v[36:39]
	v_mfma_f32_16x16x32_bf16 v[6:9], v[204:207], v[196:199], v[6:9]
	v_mfma_f32_16x16x32_bf16 v[2:5], v[212:215], v[196:199], v[2:5]
	v_mfma_f32_16x16x32_bf16 v[72:75], v[208:211], v[176:179], v[72:75]
	v_mfma_f32_16x16x32_bf16 v[68:71], v[216:219], v[176:179], v[68:71]
	v_mfma_f32_16x16x32_bf16 v[56:59], v[208:211], v[184:187], v[56:59]
	v_mfma_f32_16x16x32_bf16 v[52:55], v[216:219], v[184:187], v[52:55]
	v_mfma_f32_16x16x32_bf16 v[40:43], v[208:211], v[192:195], v[40:43]
	v_mfma_f32_16x16x32_bf16 v[36:39], v[216:219], v[192:195], v[36:39]
	v_mfma_f32_16x16x32_bf16 v[6:9], v[208:211], v[200:203], v[6:9]
	v_mfma_f32_16x16x32_bf16 v[2:5], v[216:219], v[200:203], v[2:5]
	s_setprio 0
	s_add_i32 s59, s59, 2
	s_add_u32 s57, s57, 0x100
	s_addc_u32 s58, s58, 0
	s_cmp_gt_u32 s59, 13
	s_mov_b64 s[16:17], s[36:37]
	s_barrier
	s_cbranch_scc0 .LBB0_538
	s_lshr_b32 s16, s53, 6
	s_mulk_i32 s16, 0x1800
	v_lshl_add_u32 v170, s53, 8, v172
	v_lshl_or_b32 v168, s54, 8, v174
	s_ashr_i32 s17, s16, 31
	v_ashrrev_i32_e32 v171, 31, v170
	s_lshl_b64 s[16:17], s[16:17], 2
	v_ashrrev_i32_e32 v169, 31, v168
	v_lshlrev_b64 v[176:177], 10, v[170:171]
	s_add_u32 s16, s38, s16
	v_lshl_add_u64 v[176:177], v[176:177], 0, v[168:169]
	s_addc_u32 s17, s39, s17
	v_lshlrev_b64 v[192:193], 2, v[176:177]
	v_lshl_add_u64 v[100:101], v[168:169], 2, s[16:17]
	v_lshl_add_u64 v[188:189], s[24:25], 0, v[192:193]
	v_mov_b32_e32 v168, v192
	v_mov_b32_e32 v169, v193
	global_load_dwordx4 v[112:115], v[100:101], off
	global_load_dwordx4 v[108:111], v[100:101], off offset:64
	global_load_dwordx4 v[104:107], v[100:101], off offset:512
	s_nop 0
	global_load_dwordx4 v[100:103], v[100:101], off offset:576
	s_add_u32 s98, s24, 0x0
	s_addc_u32 s99, s25, 0
	v_lshl_add_u64 v[170:171], v[168:169], 0, s[98:99]
	global_load_dwordx4 v[176:179], v[170:171], off
	global_load_dwordx4 v[180:183], v[170:171], off offset:64
	global_load_dwordx4 v[184:187], v[170:171], off offset:512
	global_load_dwordx4 v[188:191], v[170:171], off offset:576
	s_add_u32 s98, s24, 0x10000
	s_addc_u32 s99, s25, 0
	v_lshl_add_u64 v[170:171], v[168:169], 0, s[98:99]
	global_load_dwordx4 v[192:195], v[170:171], off
	global_load_dwordx4 v[196:199], v[170:171], off offset:64
	global_load_dwordx4 v[200:203], v[170:171], off offset:512
	global_load_dwordx4 v[204:207], v[170:171], off offset:576
	s_add_u32 s98, s24, 0x20000
	s_addc_u32 s99, s25, 0
	v_lshl_add_u64 v[170:171], v[168:169], 0, s[98:99]
	global_load_dwordx4 v[208:211], v[170:171], off
	global_load_dwordx4 v[212:215], v[170:171], off offset:64
	global_load_dwordx4 v[216:219], v[170:171], off offset:512
	global_load_dwordx4 v[220:223], v[170:171], off offset:576
	s_and_b64 vcc, exec, s[40:41]
	s_mov_b32 s54, s30
	s_mov_b32 s53, s34
	s_mov_b64 s[36:37], s[44:45]
	s_mov_b64 s[16:17], s[42:43]
	s_waitcnt vmcnt(8)
;   DI void operator()(const f32x4 (&acc)[2][2][4][2], const pg8::Unit& u, int wr, int wc, int fr, int fq) const {
;     ...
;     for (int ai = 0; ai < 2; ++ai)
; #pragma unroll
;       for (int m = 0; m < 4; ++m) {
;         const size_t off = (size_t)(u.pm * 256 + ai * 128 + wr * 64 + m * 16 + fr) * 1024 + col0;
;         f32x4 xo[2][2];
; #pragma unroll
;         for (int bj = 0; bj < 2; ++bj)
; #pragma unroll
;           for (int n = 0; n < 2; ++n) xo[bj][n] = *(const f32x4*)(xold + off + bj * 128 + n * 16);
; #pragma unroll
;         for (int bj = 0; bj < 2; ++bj)
; #pragma unroll
;           for (int n = 0; n < 2; ++n) *(f32x4*)(xnew + off + bj * 128 + n * 16) = xo[bj][n] + gv[bj][n] * acc[ai][bj][m][n];
	v_pk_fma_f32 v[160:161], v[160:161], v[112:113], v[176:177]
	v_pk_fma_f32 v[162:163], v[162:163], v[114:115], v[178:179]
	v_pk_fma_f32 v[156:157], v[156:157], v[108:109], v[180:181]
	v_pk_fma_f32 v[158:159], v[158:159], v[110:111], v[182:183]
	v_pk_fma_f32 v[152:153], v[152:153], v[104:105], v[184:185]
	v_pk_fma_f32 v[154:155], v[154:155], v[106:107], v[186:187]
	v_pk_fma_f32 v[148:149], v[148:149], v[100:101], v[188:189]
	v_pk_fma_f32 v[150:151], v[150:151], v[102:103], v[190:191]
	s_add_u32 s98, s24, 0x30000
	s_addc_u32 s99, s25, 0
	v_lshl_add_u64 v[170:171], v[168:169], 0, s[98:99]
	global_load_dwordx4 v[176:179], v[170:171], off
	global_load_dwordx4 v[180:183], v[170:171], off offset:64
	global_load_dwordx4 v[184:187], v[170:171], off offset:512
	global_load_dwordx4 v[188:191], v[170:171], off offset:576
	s_waitcnt vmcnt(8)
	v_pk_fma_f32 v[144:145], v[144:145], v[112:113], v[192:193]
	v_pk_fma_f32 v[146:147], v[146:147], v[114:115], v[194:195]
	v_pk_fma_f32 v[140:141], v[140:141], v[108:109], v[196:197]
	v_pk_fma_f32 v[142:143], v[142:143], v[110:111], v[198:199]
	v_pk_fma_f32 v[136:137], v[136:137], v[104:105], v[200:201]
	v_pk_fma_f32 v[138:139], v[138:139], v[106:107], v[202:203]
	v_pk_fma_f32 v[132:133], v[132:133], v[100:101], v[204:205]
	v_pk_fma_f32 v[134:135], v[134:135], v[102:103], v[206:207]
	s_add_u32 s98, s24, 0x80000
	s_addc_u32 s99, s25, 0
	v_lshl_add_u64 v[170:171], v[168:169], 0, s[98:99]
	global_load_dwordx4 v[192:195], v[170:171], off
	global_load_dwordx4 v[196:199], v[170:171], off offset:64
	global_load_dwordx4 v[200:203], v[170:171], off offset:512
	global_load_dwordx4 v[204:207], v[170:171], off offset:576
	s_waitcnt vmcnt(8)
	v_pk_fma_f32 v[128:129], v[128:129], v[112:113], v[208:209]
	v_pk_fma_f32 v[130:131], v[130:131], v[114:115], v[210:211]
	v_pk_fma_f32 v[124:125], v[124:125], v[108:109], v[212:213]
	v_pk_fma_f32 v[126:127], v[126:127], v[110:111], v[214:215]
	v_pk_fma_f32 v[120:121], v[120:121], v[104:105], v[216:217]
	v_pk_fma_f32 v[122:123], v[122:123], v[106:107], v[218:219]
	v_pk_fma_f32 v[116:117], v[116:117], v[100:101], v[220:221]
	v_pk_fma_f32 v[118:119], v[118:119], v[102:103], v[222:223]
	s_add_u32 s98, s24, 0x90000
	s_addc_u32 s99, s25, 0
	v_lshl_add_u64 v[170:171], v[168:169], 0, s[98:99]
	global_load_dwordx4 v[208:211], v[170:171], off
	global_load_dwordx4 v[212:215], v[170:171], off offset:64
	global_load_dwordx4 v[216:219], v[170:171], off offset:512
	global_load_dwordx4 v[220:223], v[170:171], off offset:576
	s_waitcnt vmcnt(8)
	v_pk_fma_f32 v[96:97], v[96:97], v[112:113], v[176:177]
	v_pk_fma_f32 v[98:99], v[98:99], v[114:115], v[178:179]
	v_pk_fma_f32 v[92:93], v[92:93], v[108:109], v[180:181]
	v_pk_fma_f32 v[94:95], v[94:95], v[110:111], v[182:183]
	v_pk_fma_f32 v[88:89], v[88:89], v[104:105], v[184:185]
	v_pk_fma_f32 v[90:91], v[90:91], v[106:107], v[186:187]
	v_pk_fma_f32 v[84:85], v[84:85], v[100:101], v[188:189]
	v_pk_fma_f32 v[86:87], v[86:87], v[102:103], v[190:191]
	s_add_u32 s98, s24, 0xa0000
	s_addc_u32 s99, s25, 0
	v_lshl_add_u64 v[170:171], v[168:169], 0, s[98:99]
	global_load_dwordx4 v[176:179], v[170:171], off
	global_load_dwordx4 v[180:183], v[170:171], off offset:64
	global_load_dwordx4 v[184:187], v[170:171], off offset:512
	global_load_dwordx4 v[188:191], v[170:171], off offset:576
	s_waitcnt vmcnt(8)
	v_pk_fma_f32 v[80:81], v[80:81], v[112:113], v[192:193]
	v_pk_fma_f32 v[82:83], v[82:83], v[114:115], v[194:195]
	v_pk_fma_f32 v[76:77], v[76:77], v[108:109], v[196:197]
	v_pk_fma_f32 v[78:79], v[78:79], v[110:111], v[198:199]
	v_pk_fma_f32 v[72:73], v[72:73], v[104:105], v[200:201]
	v_pk_fma_f32 v[74:75], v[74:75], v[106:107], v[202:203]
	v_pk_fma_f32 v[68:69], v[68:69], v[100:101], v[204:205]
	v_pk_fma_f32 v[70:71], v[70:71], v[102:103], v[206:207]
	s_add_u32 s98, s24, 0xb0000
	s_addc_u32 s99, s25, 0
	v_lshl_add_u64 v[170:171], v[168:169], 0, s[98:99]
	global_load_dwordx4 v[192:195], v[170:171], off
	global_load_dwordx4 v[196:199], v[170:171], off offset:64
	global_load_dwordx4 v[200:203], v[170:171], off offset:512
	global_load_dwordx4 v[204:207], v[170:171], off offset:576
	s_waitcnt vmcnt(8)
;   DI void operator()(const f32x4 (&acc)[2][2][4][2], const pg8::Unit& u, int wr, int wc, int fr, int fq) const {
;     ...
;     for (int ai = 0; ai < 2; ++ai)
; #pragma unroll
;       for (int m = 0; m < 4; ++m) {
;         const size_t off = (size_t)(u.pm * 256 + ai * 128 + wr * 64 + m * 16 + fr) * 1024 + col0;
;         f32x4 xo[2][2];
; #pragma unroll
;         for (int bj = 0; bj < 2; ++bj)
; #pragma unroll
;           for (int n = 0; n < 2; ++n) xo[bj][n] = *(const f32x4*)(xold + off + bj * 128 + n * 16);
; #pragma unroll
;         for (int bj = 0; bj < 2; ++bj)
; #pragma unroll
;           for (int n = 0; n < 2; ++n) *(f32x4*)(xnew + off + bj * 128 + n * 16) = xo[bj][n] + gv[bj][n] * acc[ai][bj][m][n];
;         asm volatile("" ::: "memory");
;       }
	v_pk_fma_f32 v[64:65], v[64:65], v[112:113], v[208:209]
	v_pk_fma_f32 v[66:67], v[66:67], v[114:115], v[210:211]
	v_pk_fma_f32 v[60:61], v[60:61], v[108:109], v[212:213]
	v_pk_fma_f32 v[62:63], v[62:63], v[110:111], v[214:215]
	v_pk_fma_f32 v[56:57], v[56:57], v[104:105], v[216:217]
	v_pk_fma_f32 v[58:59], v[58:59], v[106:107], v[218:219]
	v_pk_fma_f32 v[52:53], v[52:53], v[100:101], v[220:221]
	v_pk_fma_f32 v[54:55], v[54:55], v[102:103], v[222:223]
	s_waitcnt vmcnt(4)
	v_pk_fma_f32 v[48:49], v[48:49], v[112:113], v[176:177]
	v_pk_fma_f32 v[50:51], v[50:51], v[114:115], v[178:179]
	v_pk_fma_f32 v[44:45], v[44:45], v[108:109], v[180:181]
	v_pk_fma_f32 v[46:47], v[46:47], v[110:111], v[182:183]
	v_pk_fma_f32 v[40:41], v[40:41], v[104:105], v[184:185]
	v_pk_fma_f32 v[42:43], v[42:43], v[106:107], v[186:187]
	v_pk_fma_f32 v[36:37], v[36:37], v[100:101], v[188:189]
	v_pk_fma_f32 v[38:39], v[38:39], v[102:103], v[190:191]
	s_waitcnt vmcnt(0)
	v_pk_fma_f32 v[32:33], v[32:33], v[112:113], v[192:193]
	v_pk_fma_f32 v[34:35], v[34:35], v[114:115], v[194:195]
	v_pk_fma_f32 v[10:11], v[10:11], v[108:109], v[196:197]
	v_pk_fma_f32 v[12:13], v[12:13], v[110:111], v[198:199]
	v_pk_fma_f32 v[6:7], v[6:7], v[104:105], v[200:201]
	v_pk_fma_f32 v[8:9], v[8:9], v[106:107], v[202:203]
	v_pk_fma_f32 v[2:3], v[2:3], v[100:101], v[204:205]
	v_pk_fma_f32 v[4:5], v[4:5], v[102:103], v[206:207]
	s_add_u32 s98, s28, 0x0
	s_addc_u32 s99, s29, 0
	v_lshl_add_u64 v[170:171], v[168:169], 0, s[98:99]
	global_store_dwordx4 v[170:171], v[160:163], off
	global_store_dwordx4 v[170:171], v[156:159], off offset:64
	global_store_dwordx4 v[170:171], v[152:155], off offset:512
	global_store_dwordx4 v[170:171], v[148:151], off offset:576
	s_add_u32 s98, s28, 0x10000
	s_addc_u32 s99, s29, 0
	v_lshl_add_u64 v[170:171], v[168:169], 0, s[98:99]
	global_store_dwordx4 v[170:171], v[144:147], off
	global_store_dwordx4 v[170:171], v[140:143], off offset:64
	global_store_dwordx4 v[170:171], v[136:139], off offset:512
	global_store_dwordx4 v[170:171], v[132:135], off offset:576
	s_add_u32 s98, s28, 0x20000
	s_addc_u32 s99, s29, 0
	v_lshl_add_u64 v[170:171], v[168:169], 0, s[98:99]
	global_store_dwordx4 v[170:171], v[128:131], off
	global_store_dwordx4 v[170:171], v[124:127], off offset:64
	global_store_dwordx4 v[170:171], v[120:123], off offset:512
	global_store_dwordx4 v[170:171], v[116:119], off offset:576
	s_add_u32 s98, s28, 0x30000
	s_addc_u32 s99, s29, 0
	v_lshl_add_u64 v[170:171], v[168:169], 0, s[98:99]
	global_store_dwordx4 v[170:171], v[96:99], off
	global_store_dwordx4 v[170:171], v[92:95], off offset:64
	global_store_dwordx4 v[170:171], v[88:91], off offset:512
	global_store_dwordx4 v[170:171], v[84:87], off offset:576
	s_add_u32 s98, s28, 0x80000
	s_addc_u32 s99, s29, 0
	v_lshl_add_u64 v[170:171], v[168:169], 0, s[98:99]
	global_store_dwordx4 v[170:171], v[80:83], off
	global_store_dwordx4 v[170:171], v[76:79], off offset:64
	global_store_dwordx4 v[170:171], v[72:75], off offset:512
	global_store_dwordx4 v[170:171], v[68:71], off offset:576
	s_add_u32 s98, s28, 0x90000
	s_addc_u32 s99, s29, 0
	v_lshl_add_u64 v[170:171], v[168:169], 0, s[98:99]
	global_store_dwordx4 v[170:171], v[64:67], off
	global_store_dwordx4 v[170:171], v[60:63], off offset:64
	global_store_dwordx4 v[170:171], v[56:59], off offset:512
	global_store_dwordx4 v[170:171], v[52:55], off offset:576
	s_add_u32 s98, s28, 0xa0000
	s_addc_u32 s99, s29, 0
	v_lshl_add_u64 v[170:171], v[168:169], 0, s[98:99]
	global_store_dwordx4 v[170:171], v[48:51], off
	global_store_dwordx4 v[170:171], v[44:47], off offset:64
	global_store_dwordx4 v[170:171], v[40:43], off offset:512
	global_store_dwordx4 v[170:171], v[36:39], off offset:576
	s_add_u32 s98, s28, 0xb0000
	s_addc_u32 s99, s29, 0
	v_lshl_add_u64 v[170:171], v[168:169], 0, s[98:99]
	global_store_dwordx4 v[170:171], v[32:35], off
	global_store_dwordx4 v[170:171], v[10:13], off offset:64
	global_store_dwordx4 v[170:171], v[6:9], off offset:512
	global_store_dwordx4 v[170:171], v[2:5], off offset:576
	s_cbranch_vccz .LBB0_531
	s_waitcnt vmcnt(0)
	v_readlane_b32 s48, v255, 4
	v_readlane_b32 s50, v255, 6
	s_cmpk_gt_u32 s6, 0xff
	v_readlane_b32 s49, v255, 5
	v_readlane_b32 s51, v255, 7
	s_cbranch_scc1 .LBB0_542
	s_barrier

; #define PG8_STAGE(bufoff, gbase, voff) do { _Pragma("unroll") for (int _i = 0; _i < 2; ++_i) \
;         __builtin_amdgcn_global_load_lds((const unsigned*)((const char*)(gbase) + (voff)[_i]), (LAS unsigned*)(lds + (bufoff) + ldsw + _i * 8192), 16, 0, 0); } while (0)
; #define PG8_LDA(dst, b, h) do { _Pragma("unroll") for (int m = 0; m < 4; ++m) _Pragma("unroll") for (int k = 0; k < 2; ++k) dst[m][k] = *(const LAS bf16x8*)(lds + PG8_SA(b, h) + aoff + m * 2048 + k * 1024); } while (0)
; #define PG8_LDB(dst, b, h) do { _Pragma("unroll") for (int n = 0; n < 2; ++n) _Pragma("unroll") for (int k = 0; k < 2; ++k) dst[n][k] = *(const LAS bf16x8*)(lds + PG8_SB(b, h) + boff + n * 2048 + k * 1024); } while (0)
; #define PG8_MMA(ai, bj, At, Bt) do { __builtin_amdgcn_s_setprio(1); _Pragma("unroll") for (int m = 0; m < 4; ++m) _Pragma("unroll") for (int n = 0; n < 2; ++n) _Pragma("unroll") for (int k = 0; k < 2; ++k) \
;         acc[ai][bj][m][n] = __builtin_amdgcn_mfma_f32_16x16x32_bf16(Bt[n][k], At[m][k], acc[ai][bj][m][n], 0, 0, 0); __builtin_amdgcn_s_setprio(0); } while (0)
; #define PG8_BAR __builtin_amdgcn_s_barrier()
; template <class AMap, class Epi>
; DI void gemm_phase(LAS unsigned char* lds, const u16* Aptr, const u16* Btptr, int K, const StaticOrder& SO, const Epi& E) {
;     ...
;     for (int t = 0; t < nt; t += 2) {
;       const bool last = (t == nt - 2);
;       const char* a1 = cA + (size_t)(t + 1) * kstep;
;       const char* a2 = last ? nA : cA + (size_t)(t + 2) * kstep; const char* b2 = last ? nB : cB + (size_t)(t + 2) * kstep;
;       const char* a3 = a2 + kstep; const char* b3 = b2 + kstep;
;       PG8_LDB(B0, 0, 0); PG8_SCHED; PG8_LDA(At, 0, 0); PG8_STAGE(PG8_SA(1, 1), a1 + hstepA, voffA);
;       PG8_WAIT_L(8); PG8_BAR; PG8_WAIT_L(0); PG8_MMA(0, 0, At, B0); PG8_BAR; PG8_SCHED;
;       PG8_LDB(B1, 0, 1); PG8_STAGE(PG8_SB(0, 0), b2, voffB);
;       PG8_BAR; PG8_WAIT_L(0); PG8_MMA(0, 1, At, B1); PG8_BAR;
;       PG8_LDA(At, 0, 1); PG8_STAGE(PG8_SA(0, 0), a2, voffA);
;       PG8_BAR; PG8_WAIT_L(0); PG8_MMA(1, 0, At, B0); PG8_BAR; PG8_SCHED;
;       PG8_STAGE(PG8_SB(0, 1), b2 + hstepB, voffB);
;       PG8_WAIT_V(6); PG8_BAR; PG8_MMA(1, 1, At, B1); PG8_BAR;
;       PG8_LDB(B0, 1, 0); PG8_SCHED; PG8_LDA(At, 1, 0); PG8_STAGE(PG8_SA(0, 1), a2 + hstepA, voffA);
;       PG8_WAIT_L(8); PG8_BAR; PG8_WAIT_L(0); PG8_MMA(0, 0, At, B0); PG8_BAR; PG8_SCHED;
.LBB0_785:
	s_add_u32 s26, s16, 0x100
	s_addc_u32 s27, s17, 0
	s_add_i32 s43, 0, 0x10000
	v_add_u32_e32 v112, s43, v173
	ds_read_b128 v[100:103], v112
	ds_read_b128 v[104:107], v112 offset:1024
	ds_read_b128 v[108:111], v112 offset:2048
	ds_read_b128 v[112:115], v112 offset:3072
	s_cmp_eq_u32 s42, 40
	s_cselect_b32 s31, s19, s27
	s_cselect_b32 s30, s18, s26
	s_cselect_b32 s29, s25, s41
	s_cselect_b32 s28, s24, s40
	v_lshl_add_u64 v[204:205], s[16:17], 0, v[164:165]
	s_add_i32 m0, s35, 0xc000
	ds_read_b128 v[168:171], v175
	ds_read_b128 v[176:179], v175 offset:1024
	ds_read_b128 v[180:183], v175 offset:2048
	ds_read_b128 v[184:187], v175 offset:3072
	ds_read_b128 v[188:191], v175 offset:4096
	ds_read_b128 v[192:195], v175 offset:5120
	ds_read_b128 v[196:199], v175 offset:6144
	ds_read_b128 v[200:203], v175 offset:7168
	global_load_lds_dwordx4 v[204:205], off
	v_lshl_add_u64 v[204:205], s[16:17], 0, v[166:167]
	s_add_i32 m0, s35, 0xe000
	s_nop 0
	global_load_lds_dwordx4 v[204:205], off
	s_waitcnt lgkmcnt(8)
	s_barrier
	s_waitcnt lgkmcnt(0)
	s_setprio 1
	s_waitcnt lgkmcnt(0)
	v_mfma_f32_16x16x32_bf16 v[160:163], v[100:103], v[168:171], v[160:163]
	v_mfma_f32_16x16x32_bf16 v[156:159], v[108:111], v[168:171], v[156:159]
	v_mfma_f32_16x16x32_bf16 v[144:147], v[100:103], v[180:183], v[144:147]
	v_mfma_f32_16x16x32_bf16 v[140:143], v[108:111], v[180:183], v[140:143]
	v_mfma_f32_16x16x32_bf16 v[128:131], v[100:103], v[188:191], v[128:131]
	v_mfma_f32_16x16x32_bf16 v[124:127], v[108:111], v[188:191], v[124:127]
	v_mfma_f32_16x16x32_bf16 v[96:99], v[100:103], v[196:199], v[96:99]
	v_mfma_f32_16x16x32_bf16 v[92:95], v[108:111], v[196:199], v[92:95]
	v_mfma_f32_16x16x32_bf16 v[160:163], v[104:107], v[176:179], v[160:163]
	v_mfma_f32_16x16x32_bf16 v[156:159], v[112:115], v[176:179], v[156:159]
	v_mfma_f32_16x16x32_bf16 v[144:147], v[104:107], v[184:187], v[144:147]
	v_mfma_f32_16x16x32_bf16 v[140:143], v[112:115], v[184:187], v[140:143]
	v_mfma_f32_16x16x32_bf16 v[128:131], v[104:107], v[192:195], v[128:131]
	v_mfma_f32_16x16x32_bf16 v[124:127], v[112:115], v[192:195], v[124:127]
	v_mfma_f32_16x16x32_bf16 v[96:99], v[104:107], v[200:203], v[96:99]
	v_mfma_f32_16x16x32_bf16 v[92:95], v[112:115], v[200:203], v[92:95]
	s_setprio 0
	s_barrier
	s_add_i32 s54, 0, 0x14000
	s_add_i32 s16, s43, s34
	v_add_u32_e32 v216, s54, v173
	v_lshl_add_u64 v[220:221], s[28:29], 0, v[0:1]
	s_mov_b32 m0, s16
	ds_read_b128 v[204:207], v216
	ds_read_b128 v[208:211], v216 offset:1024
	ds_read_b128 v[212:215], v216 offset:2048
	ds_read_b128 v[216:219], v216 offset:3072
	global_load_lds_dwordx4 v[220:221], off
	v_lshl_add_u64 v[222:223], s[28:29], 0, v[14:15]
	s_add_i32 m0, s16, 0x2000
	s_nop 0
	global_load_lds_dwordx4 v[222:223], off
	s_barrier
	s_waitcnt lgkmcnt(0)
	s_setprio 1
	s_waitcnt lgkmcnt(0)
	v_mfma_f32_16x16x32_bf16 v[152:155], v[204:207], v[168:171], v[152:155]
	v_mfma_f32_16x16x32_bf16 v[148:151], v[212:215], v[168:171], v[148:151]
	v_mfma_f32_16x16x32_bf16 v[136:139], v[204:207], v[180:183], v[136:139]
	v_mfma_f32_16x16x32_bf16 v[132:135], v[212:215], v[180:183], v[132:135]
	v_mfma_f32_16x16x32_bf16 v[120:123], v[204:207], v[188:191], v[120:123]
	v_mfma_f32_16x16x32_bf16 v[116:119], v[212:215], v[188:191], v[116:119]
	v_mfma_f32_16x16x32_bf16 v[88:91], v[204:207], v[196:199], v[88:91]
	v_mfma_f32_16x16x32_bf16 v[84:87], v[212:215], v[196:199], v[84:87]
	v_mfma_f32_16x16x32_bf16 v[152:155], v[208:211], v[176:179], v[152:155]
	v_mfma_f32_16x16x32_bf16 v[148:151], v[216:219], v[176:179], v[148:151]
	v_mfma_f32_16x16x32_bf16 v[136:139], v[208:211], v[184:187], v[136:139]
	v_mfma_f32_16x16x32_bf16 v[132:135], v[216:219], v[184:187], v[132:135]
	v_mfma_f32_16x16x32_bf16 v[120:123], v[208:211], v[192:195], v[120:123]
	v_mfma_f32_16x16x32_bf16 v[116:119], v[216:219], v[192:195], v[116:119]
	v_mfma_f32_16x16x32_bf16 v[88:91], v[208:211], v[200:203], v[88:91]
	v_mfma_f32_16x16x32_bf16 v[84:87], v[216:219], v[200:203], v[84:87]
	s_setprio 0
	s_mov_b32 m0, s35
	v_lshl_add_u64 v[234:235], s[30:31], 0, v[0:1]
	s_barrier
	ds_read_b128 v[168:171], v175 offset:16384
	ds_read_b128 v[176:179], v175 offset:17408
	ds_read_b128 v[180:183], v175 offset:18432
	ds_read_b128 v[184:187], v175 offset:19456
	ds_read_b128 v[188:191], v175 offset:20480
	ds_read_b128 v[192:195], v175 offset:21504
	ds_read_b128 v[196:199], v175 offset:22528
	ds_read_b128 v[200:203], v175 offset:23552
	global_load_lds_dwordx4 v[234:235], off
	v_lshl_add_u64 v[236:237], s[30:31], 0, v[14:15]
	s_mov_b32 m0, s36
	s_nop 0
	global_load_lds_dwordx4 v[236:237], off
	s_barrier
	s_waitcnt lgkmcnt(0)
	s_setprio 1
	s_waitcnt lgkmcnt(0)
	v_mfma_f32_16x16x32_bf16 v[80:83], v[100:103], v[168:171], v[80:83]
	v_mfma_f32_16x16x32_bf16 v[76:79], v[108:111], v[168:171], v[76:79]
	v_mfma_f32_16x16x32_bf16 v[64:67], v[100:103], v[180:183], v[64:67]
	v_mfma_f32_16x16x32_bf16 v[60:63], v[108:111], v[180:183], v[60:63]
	v_mfma_f32_16x16x32_bf16 v[48:51], v[100:103], v[188:191], v[48:51]
	v_mfma_f32_16x16x32_bf16 v[44:47], v[108:111], v[188:191], v[44:47]
	v_mfma_f32_16x16x32_bf16 v[32:35], v[100:103], v[196:199], v[32:35]
	v_mfma_f32_16x16x32_bf16 v[10:13], v[108:111], v[196:199], v[10:13]
	v_mfma_f32_16x16x32_bf16 v[80:83], v[104:107], v[176:179], v[80:83]
	v_mfma_f32_16x16x32_bf16 v[76:79], v[112:115], v[176:179], v[76:79]
	v_mfma_f32_16x16x32_bf16 v[64:67], v[104:107], v[184:187], v[64:67]
	v_mfma_f32_16x16x32_bf16 v[60:63], v[112:115], v[184:187], v[60:63]
	v_mfma_f32_16x16x32_bf16 v[48:51], v[104:107], v[192:195], v[48:51]
	v_mfma_f32_16x16x32_bf16 v[44:47], v[112:115], v[192:195], v[44:47]
	v_mfma_f32_16x16x32_bf16 v[32:35], v[104:107], v[200:203], v[32:35]
	v_mfma_f32_16x16x32_bf16 v[10:13], v[112:115], v[200:203], v[10:13]
	s_setprio 0
	s_barrier
; #define PG8_STAGE(bufoff, gbase, voff) do { _Pragma("unroll") for (int _i = 0; _i < 2; ++_i) \
;         __builtin_amdgcn_global_load_lds((const unsigned*)((const char*)(gbase) + (voff)[_i]), (LAS unsigned*)(lds + (bufoff) + ldsw + _i * 8192), 16, 0, 0); } while (0)
; #define PG8_LDA(dst, b, h) do { _Pragma("unroll") for (int m = 0; m < 4; ++m) _Pragma("unroll") for (int k = 0; k < 2; ++k) dst[m][k] = *(const LAS bf16x8*)(lds + PG8_SA(b, h) + aoff + m * 2048 + k * 1024); } while (0)
; #define PG8_LDB(dst, b, h) do { _Pragma("unroll") for (int n = 0; n < 2; ++n) _Pragma("unroll") for (int k = 0; k < 2; ++k) dst[n][k] = *(const LAS bf16x8*)(lds + PG8_SB(b, h) + boff + n * 2048 + k * 1024); } while (0)
; #define PG8_MMA(ai, bj, At, Bt) do { __builtin_amdgcn_s_setprio(1); _Pragma("unroll") for (int m = 0; m < 4; ++m) _Pragma("unroll") for (int n = 0; n < 2; ++n) _Pragma("unroll") for (int k = 0; k < 2; ++k) \
;         acc[ai][bj][m][n] = __builtin_amdgcn_mfma_f32_16x16x32_bf16(Bt[n][k], At[m][k], acc[ai][bj][m][n], 0, 0, 0); __builtin_amdgcn_s_setprio(0); } while (0)
; #define PG8_WAIT_V(n) asm volatile("s_waitcnt vmcnt(" #n ")" ::: "memory")
; #define PG8_WAIT_L(n) asm volatile("s_waitcnt lgkmcnt(" #n ")" ::: "memory")
; #define PG8_BAR __builtin_amdgcn_s_barrier()
; #define PG8_SCHED __builtin_amdgcn_sched_barrier(0)
; template <class AMap, class Epi>
; DI void gemm_phase(LAS unsigned char* lds, const u16* Aptr, const u16* Btptr, int K, const StaticOrder& SO, const Epi& E) {
;     ...
;       PG8_WAIT_V(6); PG8_BAR; PG8_MMA(1, 1, At, B1); PG8_BAR;
;       PG8_LDB(B0, 1, 0); PG8_SCHED; PG8_LDA(At, 1, 0); PG8_STAGE(PG8_SA(0, 1), a2 + hstepA, voffA);
;       PG8_WAIT_L(8); PG8_BAR; PG8_WAIT_L(0); PG8_MMA(0, 0, At, B0); PG8_BAR; PG8_SCHED;
;       PG8_LDB(B1, 1, 1); PG8_STAGE(PG8_SB(1, 0), b3, voffB);
;       PG8_BAR; PG8_WAIT_L(0); PG8_MMA(0, 1, At, B1); PG8_BAR;
;       PG8_LDA(At, 1, 1); PG8_STAGE(PG8_SA(1, 0), a3, voffA);
;       PG8_BAR; PG8_WAIT_L(0); PG8_MMA(1, 0, At, B0); PG8_BAR; PG8_SCHED;
	s_add_u32 s16, s28, 0xb0000
	s_addc_u32 s17, s29, 0
	s_add_i32 s43, s54, s34
	v_lshl_add_u64 v[100:101], s[16:17], 0, v[0:1]
	s_mov_b32 m0, s43
	s_nop 0
	global_load_lds_dwordx4 v[100:101], off
	v_lshl_add_u64 v[100:101], s[16:17], 0, v[14:15]
	s_add_i32 m0, s43, 0x2000
	s_nop 0
	global_load_lds_dwordx4 v[100:101], off
	s_waitcnt vmcnt(6)
	s_barrier
	s_setprio 1
	v_mfma_f32_16x16x32_bf16 v[72:75], v[204:207], v[168:171], v[72:75]
	v_mfma_f32_16x16x32_bf16 v[68:71], v[212:215], v[168:171], v[68:71]
	v_mfma_f32_16x16x32_bf16 v[56:59], v[204:207], v[180:183], v[56:59]
	v_mfma_f32_16x16x32_bf16 v[52:55], v[212:215], v[180:183], v[52:55]
	v_mfma_f32_16x16x32_bf16 v[40:43], v[204:207], v[188:191], v[40:43]
	v_mfma_f32_16x16x32_bf16 v[36:39], v[212:215], v[188:191], v[36:39]
	v_mfma_f32_16x16x32_bf16 v[6:9], v[204:207], v[196:199], v[6:9]
	v_mfma_f32_16x16x32_bf16 v[2:5], v[212:215], v[196:199], v[2:5]
	v_mfma_f32_16x16x32_bf16 v[72:75], v[208:211], v[176:179], v[72:75]
	v_mfma_f32_16x16x32_bf16 v[68:71], v[216:219], v[176:179], v[68:71]
	v_mfma_f32_16x16x32_bf16 v[56:59], v[208:211], v[184:187], v[56:59]
	v_mfma_f32_16x16x32_bf16 v[52:55], v[216:219], v[184:187], v[52:55]
	v_mfma_f32_16x16x32_bf16 v[40:43], v[208:211], v[192:195], v[40:43]
	v_mfma_f32_16x16x32_bf16 v[36:39], v[216:219], v[192:195], v[36:39]
	v_mfma_f32_16x16x32_bf16 v[6:9], v[208:211], v[200:203], v[6:9]
	v_mfma_f32_16x16x32_bf16 v[2:5], v[216:219], v[200:203], v[2:5]
	s_setprio 0
	s_add_i32 s43, 0, 0x18000
	v_add_u32_e32 v112, s43, v173
	s_barrier
	ds_read_b128 v[100:103], v112
	ds_read_b128 v[104:107], v112 offset:1024
	ds_read_b128 v[108:111], v112 offset:2048
	ds_read_b128 v[112:115], v112 offset:3072
	s_add_u32 s16, s30, 0xb0000
	s_addc_u32 s17, s31, 0
	s_mov_b32 m0, s37
	v_lshl_add_u64 v[204:205], s[16:17], 0, v[0:1]
	ds_read_b128 v[168:171], v175 offset:32768
	ds_read_b128 v[176:179], v175 offset:33792
	ds_read_b128 v[180:183], v175 offset:34816
	ds_read_b128 v[184:187], v175 offset:35840
	ds_read_b128 v[188:191], v175 offset:36864
	ds_read_b128 v[192:195], v175 offset:37888
	ds_read_b128 v[196:199], v175 offset:38912
	ds_read_b128 v[200:203], v175 offset:39936
	global_load_lds_dwordx4 v[204:205], off
	v_lshl_add_u64 v[204:205], s[16:17], 0, v[14:15]
	s_mov_b32 m0, s44
	s_nop 0
	global_load_lds_dwordx4 v[204:205], off
	s_waitcnt lgkmcnt(8)
	s_barrier
	s_waitcnt lgkmcnt(0)
	s_setprio 1
	s_waitcnt lgkmcnt(0)
	v_mfma_f32_16x16x32_bf16 v[160:163], v[100:103], v[168:171], v[160:163]
	v_mfma_f32_16x16x32_bf16 v[156:159], v[108:111], v[168:171], v[156:159]
	v_mfma_f32_16x16x32_bf16 v[144:147], v[100:103], v[180:183], v[144:147]
	v_mfma_f32_16x16x32_bf16 v[140:143], v[108:111], v[180:183], v[140:143]
	v_mfma_f32_16x16x32_bf16 v[128:131], v[100:103], v[188:191], v[128:131]
	v_mfma_f32_16x16x32_bf16 v[124:127], v[108:111], v[188:191], v[124:127]
	v_mfma_f32_16x16x32_bf16 v[96:99], v[100:103], v[196:199], v[96:99]
	v_mfma_f32_16x16x32_bf16 v[92:95], v[108:111], v[196:199], v[92:95]
	v_mfma_f32_16x16x32_bf16 v[160:163], v[104:107], v[176:179], v[160:163]
	v_mfma_f32_16x16x32_bf16 v[156:159], v[112:115], v[176:179], v[156:159]
	v_mfma_f32_16x16x32_bf16 v[144:147], v[104:107], v[184:187], v[144:147]
	v_mfma_f32_16x16x32_bf16 v[140:143], v[112:115], v[184:187], v[140:143]
	v_mfma_f32_16x16x32_bf16 v[128:131], v[104:107], v[192:195], v[128:131]
	v_mfma_f32_16x16x32_bf16 v[124:127], v[112:115], v[192:195], v[124:127]
	v_mfma_f32_16x16x32_bf16 v[96:99], v[104:107], v[200:203], v[96:99]
	v_mfma_f32_16x16x32_bf16 v[92:95], v[112:115], v[200:203], v[92:95]
	s_setprio 0
	s_barrier
	s_add_i32 s30, 0, 0x1c000
	s_add_i32 s16, s43, s34
	v_add_u32_e32 v216, s30, v173
	v_lshl_add_u64 v[220:221], v[220:221], 0, s[14:15]
	s_mov_b32 m0, s16
	ds_read_b128 v[204:207], v216
	ds_read_b128 v[208:211], v216 offset:1024
	ds_read_b128 v[212:215], v216 offset:2048
	ds_read_b128 v[216:219], v216 offset:3072
	global_load_lds_dwordx4 v[220:221], off
	v_lshl_add_u64 v[220:221], v[222:223], 0, s[14:15]
	s_add_i32 m0, s16, 0x2000
	s_nop 0
	global_load_lds_dwordx4 v[220:221], off
	s_barrier
	s_waitcnt lgkmcnt(0)
	s_setprio 1
	s_waitcnt lgkmcnt(0)
	v_mfma_f32_16x16x32_bf16 v[152:155], v[204:207], v[168:171], v[152:155]
	v_mfma_f32_16x16x32_bf16 v[148:151], v[212:215], v[168:171], v[148:151]
	v_mfma_f32_16x16x32_bf16 v[136:139], v[204:207], v[180:183], v[136:139]
	v_mfma_f32_16x16x32_bf16 v[132:135], v[212:215], v[180:183], v[132:135]
	v_mfma_f32_16x16x32_bf16 v[120:123], v[204:207], v[188:191], v[120:123]
	v_mfma_f32_16x16x32_bf16 v[116:119], v[212:215], v[188:191], v[116:119]
	v_mfma_f32_16x16x32_bf16 v[88:91], v[204:207], v[196:199], v[88:91]
	v_mfma_f32_16x16x32_bf16 v[84:87], v[212:215], v[196:199], v[84:87]
	v_mfma_f32_16x16x32_bf16 v[152:155], v[208:211], v[176:179], v[152:155]
	v_mfma_f32_16x16x32_bf16 v[148:151], v[216:219], v[176:179], v[148:151]
	v_mfma_f32_16x16x32_bf16 v[136:139], v[208:211], v[184:187], v[136:139]
	v_mfma_f32_16x16x32_bf16 v[132:135], v[216:219], v[184:187], v[132:135]
	v_mfma_f32_16x16x32_bf16 v[120:123], v[208:211], v[192:195], v[120:123]
	v_mfma_f32_16x16x32_bf16 v[116:119], v[216:219], v[192:195], v[116:119]
	v_mfma_f32_16x16x32_bf16 v[88:91], v[208:211], v[200:203], v[88:91]
	v_mfma_f32_16x16x32_bf16 v[84:87], v[216:219], v[200:203], v[84:87]
	s_setprio 0
	s_mov_b32 m0, s47
	v_lshl_add_u64 v[220:221], v[234:235], 0, s[14:15]
	s_barrier
; #define PG8_STAGE(bufoff, gbase, voff) do { _Pragma("unroll") for (int _i = 0; _i < 2; ++_i) \
;         __builtin_amdgcn_global_load_lds((const unsigned*)((const char*)(gbase) + (voff)[_i]), (LAS unsigned*)(lds + (bufoff) + ldsw + _i * 8192), 16, 0, 0); } while (0)
; #define PG8_LDA(dst, b, h) do { _Pragma("unroll") for (int m = 0; m < 4; ++m) _Pragma("unroll") for (int k = 0; k < 2; ++k) dst[m][k] = *(const LAS bf16x8*)(lds + PG8_SA(b, h) + aoff + m * 2048 + k * 1024); } while (0)
; #define PG8_MMA(ai, bj, At, Bt) do { __builtin_amdgcn_s_setprio(1); _Pragma("unroll") for (int m = 0; m < 4; ++m) _Pragma("unroll") for (int n = 0; n < 2; ++n) _Pragma("unroll") for (int k = 0; k < 2; ++k) \
;         acc[ai][bj][m][n] = __builtin_amdgcn_mfma_f32_16x16x32_bf16(Bt[n][k], At[m][k], acc[ai][bj][m][n], 0, 0, 0); __builtin_amdgcn_s_setprio(0); } while (0)
; #define PG8_WAIT_V(n) asm volatile("s_waitcnt vmcnt(" #n ")" ::: "memory")
; #define PG8_WAIT_L(n) asm volatile("s_waitcnt lgkmcnt(" #n ")" ::: "memory")
; #define PG8_BAR __builtin_amdgcn_s_barrier()
; template <class AMap, class Epi>
; DI void gemm_phase(LAS unsigned char* lds, const u16* Aptr, const u16* Btptr, int K, const StaticOrder& SO, const Epi& E) {
;     ...
;       PG8_BAR; PG8_WAIT_L(0); PG8_MMA(0, 1, At, B1); PG8_BAR;
;       PG8_LDA(At, 1, 1); PG8_STAGE(PG8_SA(1, 0), a3, voffA);
;       PG8_BAR; PG8_WAIT_L(0); PG8_MMA(1, 0, At, B0); PG8_BAR; PG8_SCHED;
;       PG8_STAGE(PG8_SB(1, 1), b3 + hstepB, voffB);
;       PG8_WAIT_V(6); PG8_BAR; PG8_MMA(1, 1, At, B1); PG8_BAR;
;   DI void operator()(const f32x4 (&acc)[2][2][4][2], const pg8::Unit& u, int wr, int wc, int fr, int fq) const {
;     const int b = (u.pm * 256) >> 14;
;     const int col0 = u.pn * 256 + wc * 32 + 4 * fq;
;     f32x4 gv[2][2];
; #pragma unroll
;     for (int bj = 0; bj < 2; ++bj)
; #pragma unroll
;       for (int n = 0; n < 2; ++n) gv[bj][n] = *(const f32x4*)(gate + b * 6144 + col0 + bj * 128 + n * 16);
; #pragma unroll
;     for (int ai = 0; ai < 2; ++ai)
; #pragma unroll
;       for (int m = 0; m < 4; ++m) {
;         const size_t off = (size_t)(u.pm * 256 + ai * 128 + wr * 64 + m * 16 + fr) * 1024 + col0;
;         f32x4 xo[2][2];
; #pragma unroll
;         for (int bj = 0; bj < 2; ++bj)
; #pragma unroll
;           for (int n = 0; n < 2; ++n) xo[bj][n] = *(const f32x4*)(xold + off + bj * 128 + n * 16);
	ds_read_b128 v[168:171], v175 offset:49152
	ds_read_b128 v[176:179], v175 offset:50176
	ds_read_b128 v[180:183], v175 offset:51200
	ds_read_b128 v[184:187], v175 offset:52224
	ds_read_b128 v[188:191], v175 offset:53248
	ds_read_b128 v[192:195], v175 offset:54272
	ds_read_b128 v[196:199], v175 offset:55296
	ds_read_b128 v[200:203], v175 offset:56320
	global_load_lds_dwordx4 v[220:221], off
	v_lshl_add_u64 v[220:221], v[236:237], 0, s[14:15]
	s_mov_b32 m0, s48
	s_nop 0
	global_load_lds_dwordx4 v[220:221], off
	s_barrier
	s_waitcnt lgkmcnt(0)
	s_setprio 1
	s_waitcnt lgkmcnt(0)
	v_mfma_f32_16x16x32_bf16 v[80:83], v[100:103], v[168:171], v[80:83]
	v_mfma_f32_16x16x32_bf16 v[76:79], v[108:111], v[168:171], v[76:79]
	v_mfma_f32_16x16x32_bf16 v[64:67], v[100:103], v[180:183], v[64:67]
	v_mfma_f32_16x16x32_bf16 v[60:63], v[108:111], v[180:183], v[60:63]
	v_mfma_f32_16x16x32_bf16 v[48:51], v[100:103], v[188:191], v[48:51]
	v_mfma_f32_16x16x32_bf16 v[44:47], v[108:111], v[188:191], v[44:47]
	v_mfma_f32_16x16x32_bf16 v[32:35], v[100:103], v[196:199], v[32:35]
	v_mfma_f32_16x16x32_bf16 v[10:13], v[108:111], v[196:199], v[10:13]
	v_mfma_f32_16x16x32_bf16 v[80:83], v[104:107], v[176:179], v[80:83]
	v_mfma_f32_16x16x32_bf16 v[76:79], v[112:115], v[176:179], v[76:79]
	v_mfma_f32_16x16x32_bf16 v[64:67], v[104:107], v[184:187], v[64:67]
	v_mfma_f32_16x16x32_bf16 v[60:63], v[112:115], v[184:187], v[60:63]
	v_mfma_f32_16x16x32_bf16 v[48:51], v[104:107], v[192:195], v[48:51]
	v_mfma_f32_16x16x32_bf16 v[44:47], v[112:115], v[192:195], v[44:47]
	v_mfma_f32_16x16x32_bf16 v[32:35], v[104:107], v[200:203], v[32:35]
	v_mfma_f32_16x16x32_bf16 v[10:13], v[112:115], v[200:203], v[10:13]
	s_setprio 0
	s_barrier
	s_add_u32 s16, s28, 0xb0080
	s_addc_u32 s17, s29, 0
	s_add_i32 s28, s30, s34
	v_lshl_add_u64 v[100:101], s[16:17], 0, v[0:1]
	s_mov_b32 m0, s28
	s_nop 0
	global_load_lds_dwordx4 v[100:101], off
	v_lshl_add_u64 v[100:101], s[16:17], 0, v[14:15]
	s_add_i32 m0, s28, 0x2000
	s_nop 0
	global_load_lds_dwordx4 v[100:101], off
	s_waitcnt vmcnt(6)
	s_barrier
	s_setprio 1
	v_mfma_f32_16x16x32_bf16 v[72:75], v[204:207], v[168:171], v[72:75]
	v_mfma_f32_16x16x32_bf16 v[68:71], v[212:215], v[168:171], v[68:71]
	v_mfma_f32_16x16x32_bf16 v[56:59], v[204:207], v[180:183], v[56:59]
	v_mfma_f32_16x16x32_bf16 v[52:55], v[212:215], v[180:183], v[52:55]
	v_mfma_f32_16x16x32_bf16 v[40:43], v[204:207], v[188:191], v[40:43]
	v_mfma_f32_16x16x32_bf16 v[36:39], v[212:215], v[188:191], v[36:39]
	v_mfma_f32_16x16x32_bf16 v[6:9], v[204:207], v[196:199], v[6:9]
	v_mfma_f32_16x16x32_bf16 v[2:5], v[212:215], v[196:199], v[2:5]
	v_mfma_f32_16x16x32_bf16 v[72:75], v[208:211], v[176:179], v[72:75]
	v_mfma_f32_16x16x32_bf16 v[68:71], v[216:219], v[176:179], v[68:71]
	v_mfma_f32_16x16x32_bf16 v[56:59], v[208:211], v[184:187], v[56:59]
	v_mfma_f32_16x16x32_bf16 v[52:55], v[216:219], v[184:187], v[52:55]
	v_mfma_f32_16x16x32_bf16 v[40:43], v[208:211], v[192:195], v[40:43]
	v_mfma_f32_16x16x32_bf16 v[36:39], v[216:219], v[192:195], v[36:39]
	v_mfma_f32_16x16x32_bf16 v[6:9], v[208:211], v[200:203], v[6:9]
	v_mfma_f32_16x16x32_bf16 v[2:5], v[216:219], v[200:203], v[2:5]
	s_setprio 0
	s_add_i32 s42, s42, 2
	s_add_u32 s40, s40, 0x100
	s_addc_u32 s41, s41, 0
	s_cmp_gt_u32 s42, 41
	s_mov_b64 s[16:17], s[26:27]
	s_barrier
	s_cbranch_scc0 .LBB0_785
	s_lshr_b32 s16, s52, 6
	s_mulk_i32 s16, 0x1800
	s_ashr_i32 s17, s16, 31
	v_lshl_add_u32 v170, s52, 8, v172
	v_lshl_or_b32 v100, s53, 8, v174
	s_lshl_b64 s[16:17], s[16:17], 2
	v_ashrrev_i32_e32 v171, 31, v170
	s_add_u32 s16, s45, s16
	v_ashrrev_i32_e32 v101, 31, v100
	v_lshlrev_b64 v[176:177], 12, v[170:171]
	s_addc_u32 s17, s46, s17
	v_lshlrev_b64 v[168:169], 2, v[100:101]
	v_lshl_add_u64 v[176:177], s[20:21], 0, v[176:177]
	v_lshl_add_u64 v[100:101], s[16:17], 0, v[168:169]
	v_lshl_add_u64 v[192:193], v[176:177], 0, v[168:169]
	v_mov_b32_e32 v168, v192
	v_mov_b32_e32 v169, v193
	global_load_dwordx4 v[112:115], v[100:101], off
	global_load_dwordx4 v[108:111], v[100:101], off offset:64
	global_load_dwordx4 v[104:107], v[100:101], off offset:512
	s_nop 0
	global_load_dwordx4 v[100:103], v[100:101], off offset:576
	s_mov_b32 s98, 0x0
	s_mov_b32 s99, 0
	v_lshl_add_u64 v[170:171], v[168:169], 0, s[98:99]
	global_load_dwordx4 v[176:179], v[170:171], off
	global_load_dwordx4 v[180:183], v[170:171], off offset:64
	global_load_dwordx4 v[184:187], v[170:171], off offset:512
	global_load_dwordx4 v[188:191], v[170:171], off offset:576
	s_mov_b32 s98, 0x10000
	s_mov_b32 s99, 0
	v_lshl_add_u64 v[170:171], v[168:169], 0, s[98:99]
	global_load_dwordx4 v[192:195], v[170:171], off
	global_load_dwordx4 v[196:199], v[170:171], off offset:64
	global_load_dwordx4 v[200:203], v[170:171], off offset:512
	global_load_dwordx4 v[204:207], v[170:171], off offset:576
	s_mov_b32 s98, 0x20000
	s_mov_b32 s99, 0
	v_lshl_add_u64 v[170:171], v[168:169], 0, s[98:99]
	global_load_dwordx4 v[208:211], v[170:171], off
	global_load_dwordx4 v[212:215], v[170:171], off offset:64
	global_load_dwordx4 v[216:219], v[170:171], off offset:512
	global_load_dwordx4 v[220:223], v[170:171], off offset:576
	s_and_b64 vcc, exec, s[38:39]
	s_mov_b32 s53, s50
	s_mov_b32 s52, s51
	s_mov_b64 s[26:27], s[24:25]
	s_mov_b64 s[16:17], s[18:19]
	s_waitcnt vmcnt(8)
;   DI void operator()(const f32x4 (&acc)[2][2][4][2], const pg8::Unit& u, int wr, int wc, int fr, int fq) const {
;     ...
;     for (int ai = 0; ai < 2; ++ai)
; #pragma unroll
;       for (int m = 0; m < 4; ++m) {
;         const size_t off = (size_t)(u.pm * 256 + ai * 128 + wr * 64 + m * 16 + fr) * 1024 + col0;
;         f32x4 xo[2][2];
; #pragma unroll
;         for (int bj = 0; bj < 2; ++bj)
; #pragma unroll
;           for (int n = 0; n < 2; ++n) xo[bj][n] = *(const f32x4*)(xold + off + bj * 128 + n * 16);
; #pragma unroll
;         for (int bj = 0; bj < 2; ++bj)
; #pragma unroll
;           for (int n = 0; n < 2; ++n) *(f32x4*)(xnew + off + bj * 128 + n * 16) = xo[bj][n] + gv[bj][n] * acc[ai][bj][m][n];
	v_pk_fma_f32 v[160:161], v[160:161], v[112:113], v[176:177]
	v_pk_fma_f32 v[162:163], v[162:163], v[114:115], v[178:179]
	v_pk_fma_f32 v[156:157], v[156:157], v[108:109], v[180:181]
	v_pk_fma_f32 v[158:159], v[158:159], v[110:111], v[182:183]
	v_pk_fma_f32 v[152:153], v[152:153], v[104:105], v[184:185]
	v_pk_fma_f32 v[154:155], v[154:155], v[106:107], v[186:187]
	v_pk_fma_f32 v[148:149], v[148:149], v[100:101], v[188:189]
	v_pk_fma_f32 v[150:151], v[150:151], v[102:103], v[190:191]
	s_mov_b32 s98, 0x30000
	s_mov_b32 s99, 0
	v_lshl_add_u64 v[170:171], v[168:169], 0, s[98:99]
	global_load_dwordx4 v[176:179], v[170:171], off
	global_load_dwordx4 v[180:183], v[170:171], off offset:64
	global_load_dwordx4 v[184:187], v[170:171], off offset:512
	global_load_dwordx4 v[188:191], v[170:171], off offset:576
	s_waitcnt vmcnt(8)
	v_pk_fma_f32 v[144:145], v[144:145], v[112:113], v[192:193]
	v_pk_fma_f32 v[146:147], v[146:147], v[114:115], v[194:195]
	v_pk_fma_f32 v[140:141], v[140:141], v[108:109], v[196:197]
	v_pk_fma_f32 v[142:143], v[142:143], v[110:111], v[198:199]
	v_pk_fma_f32 v[136:137], v[136:137], v[104:105], v[200:201]
	v_pk_fma_f32 v[138:139], v[138:139], v[106:107], v[202:203]
	v_pk_fma_f32 v[132:133], v[132:133], v[100:101], v[204:205]
	v_pk_fma_f32 v[134:135], v[134:135], v[102:103], v[206:207]
	s_mov_b32 s98, 0x80000
	s_mov_b32 s99, 0
	v_lshl_add_u64 v[170:171], v[168:169], 0, s[98:99]
	global_load_dwordx4 v[192:195], v[170:171], off
	global_load_dwordx4 v[196:199], v[170:171], off offset:64
	global_load_dwordx4 v[200:203], v[170:171], off offset:512
	global_load_dwordx4 v[204:207], v[170:171], off offset:576
	s_waitcnt vmcnt(8)
	v_pk_fma_f32 v[128:129], v[128:129], v[112:113], v[208:209]
	v_pk_fma_f32 v[130:131], v[130:131], v[114:115], v[210:211]
	v_pk_fma_f32 v[124:125], v[124:125], v[108:109], v[212:213]
	v_pk_fma_f32 v[126:127], v[126:127], v[110:111], v[214:215]
	v_pk_fma_f32 v[120:121], v[120:121], v[104:105], v[216:217]
	v_pk_fma_f32 v[122:123], v[122:123], v[106:107], v[218:219]
	v_pk_fma_f32 v[116:117], v[116:117], v[100:101], v[220:221]
	v_pk_fma_f32 v[118:119], v[118:119], v[102:103], v[222:223]
	s_mov_b32 s98, 0x90000
	s_mov_b32 s99, 0
	v_lshl_add_u64 v[170:171], v[168:169], 0, s[98:99]
	global_load_dwordx4 v[208:211], v[170:171], off
	global_load_dwordx4 v[212:215], v[170:171], off offset:64
	global_load_dwordx4 v[216:219], v[170:171], off offset:512
	global_load_dwordx4 v[220:223], v[170:171], off offset:576
	s_waitcnt vmcnt(8)
	v_pk_fma_f32 v[96:97], v[96:97], v[112:113], v[176:177]
	v_pk_fma_f32 v[98:99], v[98:99], v[114:115], v[178:179]
	v_pk_fma_f32 v[92:93], v[92:93], v[108:109], v[180:181]
	v_pk_fma_f32 v[94:95], v[94:95], v[110:111], v[182:183]
	v_pk_fma_f32 v[88:89], v[88:89], v[104:105], v[184:185]
	v_pk_fma_f32 v[90:91], v[90:91], v[106:107], v[186:187]
	v_pk_fma_f32 v[84:85], v[84:85], v[100:101], v[188:189]
	v_pk_fma_f32 v[86:87], v[86:87], v[102:103], v[190:191]
	s_mov_b32 s98, 0xa0000
	s_mov_b32 s99, 0
	v_lshl_add_u64 v[170:171], v[168:169], 0, s[98:99]
	global_load_dwordx4 v[176:179], v[170:171], off
	global_load_dwordx4 v[180:183], v[170:171], off offset:64
	global_load_dwordx4 v[184:187], v[170:171], off offset:512
	global_load_dwordx4 v[188:191], v[170:171], off offset:576
	s_waitcnt vmcnt(8)
	v_pk_fma_f32 v[80:81], v[80:81], v[112:113], v[192:193]
	v_pk_fma_f32 v[82:83], v[82:83], v[114:115], v[194:195]
	v_pk_fma_f32 v[76:77], v[76:77], v[108:109], v[196:197]
	v_pk_fma_f32 v[78:79], v[78:79], v[110:111], v[198:199]
	v_pk_fma_f32 v[72:73], v[72:73], v[104:105], v[200:201]
	v_pk_fma_f32 v[74:75], v[74:75], v[106:107], v[202:203]
	v_pk_fma_f32 v[68:69], v[68:69], v[100:101], v[204:205]
	v_pk_fma_f32 v[70:71], v[70:71], v[102:103], v[206:207]
	s_mov_b32 s98, 0xb0000
	s_mov_b32 s99, 0
	v_lshl_add_u64 v[170:171], v[168:169], 0, s[98:99]
	global_load_dwordx4 v[192:195], v[170:171], off
	global_load_dwordx4 v[196:199], v[170:171], off offset:64
	global_load_dwordx4 v[200:203], v[170:171], off offset:512
	global_load_dwordx4 v[204:207], v[170:171], off offset:576
	s_waitcnt vmcnt(8)
;   DI void operator()(const f32x4 (&acc)[2][2][4][2], const pg8::Unit& u, int wr, int wc, int fr, int fq) const {
;     ...
;     for (int ai = 0; ai < 2; ++ai)
; #pragma unroll
;       for (int m = 0; m < 4; ++m) {
;         const size_t off = (size_t)(u.pm * 256 + ai * 128 + wr * 64 + m * 16 + fr) * 1024 + col0;
;         f32x4 xo[2][2];
; #pragma unroll
;         for (int bj = 0; bj < 2; ++bj)
; #pragma unroll
;           for (int n = 0; n < 2; ++n) xo[bj][n] = *(const f32x4*)(xold + off + bj * 128 + n * 16);
; #pragma unroll
;         for (int bj = 0; bj < 2; ++bj)
; #pragma unroll
;           for (int n = 0; n < 2; ++n) *(f32x4*)(xnew + off + bj * 128 + n * 16) = xo[bj][n] + gv[bj][n] * acc[ai][bj][m][n];
;         asm volatile("" ::: "memory");
;       }
	v_pk_fma_f32 v[64:65], v[64:65], v[112:113], v[208:209]
	v_pk_fma_f32 v[66:67], v[66:67], v[114:115], v[210:211]
	v_pk_fma_f32 v[60:61], v[60:61], v[108:109], v[212:213]
	v_pk_fma_f32 v[62:63], v[62:63], v[110:111], v[214:215]
	v_pk_fma_f32 v[56:57], v[56:57], v[104:105], v[216:217]
	v_pk_fma_f32 v[58:59], v[58:59], v[106:107], v[218:219]
	v_pk_fma_f32 v[52:53], v[52:53], v[100:101], v[220:221]
	v_pk_fma_f32 v[54:55], v[54:55], v[102:103], v[222:223]
	s_waitcnt vmcnt(4)
	v_pk_fma_f32 v[48:49], v[48:49], v[112:113], v[176:177]
	v_pk_fma_f32 v[50:51], v[50:51], v[114:115], v[178:179]
	v_pk_fma_f32 v[44:45], v[44:45], v[108:109], v[180:181]
	v_pk_fma_f32 v[46:47], v[46:47], v[110:111], v[182:183]
	v_pk_fma_f32 v[40:41], v[40:41], v[104:105], v[184:185]
	v_pk_fma_f32 v[42:43], v[42:43], v[106:107], v[186:187]
	v_pk_fma_f32 v[36:37], v[36:37], v[100:101], v[188:189]
	v_pk_fma_f32 v[38:39], v[38:39], v[102:103], v[190:191]
	s_waitcnt vmcnt(0)
	v_pk_fma_f32 v[32:33], v[32:33], v[112:113], v[192:193]
	v_pk_fma_f32 v[34:35], v[34:35], v[114:115], v[194:195]
	v_pk_fma_f32 v[10:11], v[10:11], v[108:109], v[196:197]
	v_pk_fma_f32 v[12:13], v[12:13], v[110:111], v[198:199]
	v_pk_fma_f32 v[6:7], v[6:7], v[104:105], v[200:201]
	v_pk_fma_f32 v[8:9], v[8:9], v[106:107], v[202:203]
	v_pk_fma_f32 v[2:3], v[2:3], v[100:101], v[204:205]
	v_pk_fma_f32 v[4:5], v[4:5], v[102:103], v[206:207]
	s_mov_b32 s98, 0x0
	s_mov_b32 s99, 0
	v_lshl_add_u64 v[170:171], v[168:169], 0, s[98:99]
	global_store_dwordx4 v[170:171], v[160:163], off
	global_store_dwordx4 v[170:171], v[156:159], off offset:64
	global_store_dwordx4 v[170:171], v[152:155], off offset:512
	global_store_dwordx4 v[170:171], v[148:151], off offset:576
	s_mov_b32 s98, 0x10000
	s_mov_b32 s99, 0
	v_lshl_add_u64 v[170:171], v[168:169], 0, s[98:99]
	global_store_dwordx4 v[170:171], v[144:147], off
	global_store_dwordx4 v[170:171], v[140:143], off offset:64
	global_store_dwordx4 v[170:171], v[136:139], off offset:512
	global_store_dwordx4 v[170:171], v[132:135], off offset:576
	s_mov_b32 s98, 0x20000
	s_mov_b32 s99, 0
	v_lshl_add_u64 v[170:171], v[168:169], 0, s[98:99]
	global_store_dwordx4 v[170:171], v[128:131], off
	global_store_dwordx4 v[170:171], v[124:127], off offset:64
	global_store_dwordx4 v[170:171], v[120:123], off offset:512
	global_store_dwordx4 v[170:171], v[116:119], off offset:576
	s_mov_b32 s98, 0x30000
	s_mov_b32 s99, 0
	v_lshl_add_u64 v[170:171], v[168:169], 0, s[98:99]
	global_store_dwordx4 v[170:171], v[96:99], off
	global_store_dwordx4 v[170:171], v[92:95], off offset:64
	global_store_dwordx4 v[170:171], v[88:91], off offset:512
	global_store_dwordx4 v[170:171], v[84:87], off offset:576
	s_mov_b32 s98, 0x80000
	s_mov_b32 s99, 0
	v_lshl_add_u64 v[170:171], v[168:169], 0, s[98:99]
	global_store_dwordx4 v[170:171], v[80:83], off
	global_store_dwordx4 v[170:171], v[76:79], off offset:64
	global_store_dwordx4 v[170:171], v[72:75], off offset:512
	global_store_dwordx4 v[170:171], v[68:71], off offset:576
	s_mov_b32 s98, 0x90000
	s_mov_b32 s99, 0
	v_lshl_add_u64 v[170:171], v[168:169], 0, s[98:99]
	global_store_dwordx4 v[170:171], v[64:67], off
	global_store_dwordx4 v[170:171], v[60:63], off offset:64
	global_store_dwordx4 v[170:171], v[56:59], off offset:512
	global_store_dwordx4 v[170:171], v[52:55], off offset:576
	s_mov_b32 s98, 0xa0000
	s_mov_b32 s99, 0
	v_lshl_add_u64 v[170:171], v[168:169], 0, s[98:99]
	global_store_dwordx4 v[170:171], v[48:51], off
	global_store_dwordx4 v[170:171], v[44:47], off offset:64
	global_store_dwordx4 v[170:171], v[40:43], off offset:512
	global_store_dwordx4 v[170:171], v[36:39], off offset:576
	s_mov_b32 s98, 0xb0000
	s_mov_b32 s99, 0
	v_lshl_add_u64 v[170:171], v[168:169], 0, s[98:99]
	global_store_dwordx4 v[170:171], v[32:35], off
	global_store_dwordx4 v[170:171], v[10:13], off offset:64
	global_store_dwordx4 v[170:171], v[6:9], off offset:512
	global_store_dwordx4 v[170:171], v[2:5], off offset:576
	s_cbranch_vccz .LBB0_774
	s_waitcnt vmcnt(0)
	v_readlane_b32 s48, v255, 4
	v_readlane_b32 s50, v255, 6
	s_cmpk_gt_u32 s6, 0xff
	v_readlane_b32 s49, v255, 5
	v_readlane_b32 s51, v255, 7
	s_cbranch_scc1 .LBB0_789
	s_barrier
